# tail split variant no longer stages the unused B half (2 fewer DMA per SP2, vmcnt 6)
# baseline (speedup 1.0000x reference)
; #define PG8_STAGE(bufoff, gbase, voff) do { _Pragma("unroll") for (int _i = 0; _i < 2; ++_i) \
;         __builtin_amdgcn_global_load_lds((const unsigned*)((const char*)(gbase) + (voff)[_i]), (PG8_LAS unsigned*)(lds + (bufoff) + ldsw + _i * 8192), 16, 0, 0); } while (0)
; #define PG8_LDA(dst, b, h) do { _Pragma("unroll") for (int m = 0; m < 4; ++m) _Pragma("unroll") for (int k = 0; k < 2; ++k) dst[m][k] = *(const PG8_LAS bf16x8*)(lds + PG8_SA(b, h) + aoff + m * 2048 + k * 1024); } while (0)
; #define PG8_LDB(dst, b, h) do { _Pragma("unroll") for (int n = 0; n < 2; ++n) _Pragma("unroll") for (int k = 0; k < 2; ++k) dst[n][k] = *(const PG8_LAS bf16x8*)(lds + PG8_SB(b, h) + boff + n * 2048 + k * 1024); } while (0)
; #define PG8_MMA(ai, bj, At, Bt) do { __builtin_amdgcn_s_setprio(1); _Pragma("unroll") for (int m = 0; m < 4; ++m) _Pragma("unroll") for (int n = 0; n < 2; ++n) _Pragma("unroll") for (int k = 0; k < 2; ++k) \
;         acc[ai][bj][m][n] = __builtin_amdgcn_mfma_f32_16x16x32_bf16(Bt[n][k], At[m][k], acc[ai][bj][m][n], 0, 0, 0); __builtin_amdgcn_s_setprio(0); } while (0)
; #define PG8_WAIT_V(n) asm volatile("s_waitcnt vmcnt(" #n ")" ::: "memory")
; #define PG8_WAIT_L(n) asm volatile("s_waitcnt lgkmcnt(" #n ")" ::: "memory")
; #define PG8_BAR __builtin_amdgcn_s_barrier()
; #define PG8_SCHED __builtin_amdgcn_sched_barrier(0)
; template <class Epi, class Sched, bool ALIGN_EPI = false, bool SP2 = false>
; __device__ __forceinline__ void gemm_phase(PG8_LAS unsigned char* lds, const Gemm g, const Sched& S, const Epi& E) {
;     ...
;             if constexpr (SP2) {
;             PG8_LDB(B0, 0, 0); PG8_LDB(B1, 0, 1); PG8_SCHED; PG8_LDA(At, 0, 0); PG8_STAGE(PG8_SA(1, 1), a1 + hstep, voffA);
;             PG8_WAIT_V(8); PG8_WAIT_L(0); PG8_BAR; PG8_MMA(0, 0, At, B0); PG8_MMA(0, 1, At, B1); PG8_BAR; PG8_SCHED;
;             PG8_LDA(At, 0, 1); PG8_STAGE(PG8_SB(0, 0), b2, voffB); PG8_STAGE(PG8_SB(0, 1), b2 + hstep, voffB); PG8_STAGE(PG8_SA(0, 0), a2, voffA);
;             PG8_WAIT_V(8); PG8_WAIT_L(0); PG8_BAR; PG8_MMA(1, 0, At, B0); PG8_MMA(1, 1, At, B1); PG8_BAR; PG8_SCHED;
.Ltail_loop:
	v_add_u32_e32 v134, s88, v177
	ds_read_b128 v[114:117], v134
	ds_read_b128 v[118:121], v134 offset:1024
	ds_read_b128 v[130:133], v134 offset:2048
	ds_read_b128 v[134:137], v134 offset:3072
	s_add_u32 s40, s34, 0xfff80080
	s_addc_u32 s41, s35, -1
	s_cmp_eq_u32 s46, 28
	s_cselect_b32 s43, s15, s41
	s_cselect_b32 s42, s19, s40
	s_cselect_b32 s41, s17, s45
	s_cselect_b32 s40, s37, s44
	v_lshl_add_u64 v[204:205], s[34:35], 0, v[164:165]
	s_add_i32 m0, s8, 0xc000
	ds_read_b128 v[180:183], v178
	ds_read_b128 v[184:187], v178 offset:1024
	ds_read_b128 v[188:191], v178 offset:2048
	ds_read_b128 v[192:195], v178 offset:3072
	ds_read_b128 v[196:199], v178 offset:4096
	ds_read_b128 v[200:203], v178 offset:5120
	ds_read_b128 v[208:211], v178 offset:6144
	ds_read_b128 v[230:233], v178 offset:7168
	global_load_lds_dwordx4 v[204:205], off
	v_lshl_add_u64 v[204:205], s[34:35], 0, v[166:167]
	s_add_i32 m0, s8, 0xe000
	s_nop 0
	global_load_lds_dwordx4 v[204:205], off
	s_waitcnt vmcnt(6)
	s_waitcnt lgkmcnt(0)
	s_barrier
	s_setprio 1
	s_waitcnt lgkmcnt(0)
	v_mfma_f32_16x16x32_bf16 v[142:145], v[114:117], v[180:183], v[142:145]
	v_mfma_f32_16x16x32_bf16 v[138:141], v[130:133], v[180:183], v[138:141]
	v_mfma_f32_16x16x32_bf16 v[110:113], v[114:117], v[188:191], v[110:113]
	v_mfma_f32_16x16x32_bf16 v[106:109], v[130:133], v[188:191], v[106:109]
	v_mfma_f32_16x16x32_bf16 v[94:97], v[114:117], v[196:199], v[94:97]
	v_mfma_f32_16x16x32_bf16 v[90:93], v[130:133], v[196:199], v[90:93]
	v_mfma_f32_16x16x32_bf16 v[78:81], v[114:117], v[208:211], v[78:81]
	v_mfma_f32_16x16x32_bf16 v[74:77], v[130:133], v[208:211], v[74:77]
	v_mfma_f32_16x16x32_bf16 v[142:145], v[118:121], v[184:187], v[142:145]
	v_mfma_f32_16x16x32_bf16 v[138:141], v[134:137], v[184:187], v[138:141]
	v_mfma_f32_16x16x32_bf16 v[110:113], v[118:121], v[192:195], v[110:113]
	v_mfma_f32_16x16x32_bf16 v[106:109], v[134:137], v[192:195], v[106:109]
	v_mfma_f32_16x16x32_bf16 v[94:97], v[118:121], v[200:203], v[94:97]
	v_mfma_f32_16x16x32_bf16 v[90:93], v[134:137], v[200:203], v[90:93]
	v_mfma_f32_16x16x32_bf16 v[78:81], v[118:121], v[230:233], v[78:81]
	v_mfma_f32_16x16x32_bf16 v[74:77], v[134:137], v[230:233], v[74:77]
	s_setprio 0
	s_setprio 1
	s_setprio 0
	s_barrier
	s_add_i32 s47, s88, s6
	v_lshl_add_u64 v[204:205], s[40:41], 0, v[0:1]
	s_mov_b32 m0, s47
	ds_read_b128 v[180:183], v178 offset:16384
	ds_read_b128 v[184:187], v178 offset:17408
	ds_read_b128 v[188:191], v178 offset:18432
	ds_read_b128 v[192:195], v178 offset:19456
	ds_read_b128 v[196:199], v178 offset:20480
	ds_read_b128 v[200:203], v178 offset:21504
	ds_read_b128 v[208:211], v178 offset:22528
	ds_read_b128 v[230:233], v178 offset:23552
	global_load_lds_dwordx4 v[204:205], off
	s_add_i32 m0, s47, 0x2000
	s_add_u32 s50, s40, 0x80000
	v_lshl_add_u64 v[212:213], s[40:41], 0, v[154:155]
	s_addc_u32 s51, s41, 0
	s_add_i32 s47, s89, s6
	global_load_lds_dwordx4 v[212:213], off
	v_lshl_add_u64 v[234:235], s[50:51], 0, v[0:1]
	s_mov_b32 m0, s47
	v_lshl_add_u64 v[236:237], s[42:43], 0, v[156:157]
	v_lshl_add_u64 v[234:235], s[50:51], 0, v[154:155]
	s_add_i32 m0, s47, 0x2000
	s_nop 0
	v_lshl_add_u64 v[234:235], s[42:43], 0, v[158:159]
	s_mov_b32 m0, s8
	s_nop 0
	global_load_lds_dwordx4 v[234:235], off
	s_mov_b32 m0, s9
	s_nop 0
	global_load_lds_dwordx4 v[236:237], off
	s_waitcnt vmcnt(6)
	s_waitcnt lgkmcnt(0)
	s_barrier
	s_setprio 1
	s_waitcnt lgkmcnt(0)
	v_mfma_f32_16x16x32_bf16 v[62:65], v[114:117], v[180:183], v[62:65]
	v_mfma_f32_16x16x32_bf16 v[58:61], v[130:133], v[180:183], v[58:61]
	v_mfma_f32_16x16x32_bf16 v[46:49], v[114:117], v[188:191], v[46:49]
	v_mfma_f32_16x16x32_bf16 v[42:45], v[130:133], v[188:191], v[42:45]
	v_mfma_f32_16x16x32_bf16 v[30:33], v[114:117], v[196:199], v[30:33]
	v_mfma_f32_16x16x32_bf16 v[26:29], v[130:133], v[196:199], v[26:29]
	v_mfma_f32_16x16x32_bf16 v[14:17], v[114:117], v[208:211], v[14:17]
	v_mfma_f32_16x16x32_bf16 v[10:13], v[130:133], v[208:211], v[10:13]
	v_mfma_f32_16x16x32_bf16 v[62:65], v[118:121], v[184:187], v[62:65]
	v_mfma_f32_16x16x32_bf16 v[58:61], v[134:137], v[184:187], v[58:61]
	v_mfma_f32_16x16x32_bf16 v[46:49], v[118:121], v[192:195], v[46:49]
	v_mfma_f32_16x16x32_bf16 v[42:45], v[134:137], v[192:195], v[42:45]
	v_mfma_f32_16x16x32_bf16 v[30:33], v[118:121], v[200:203], v[30:33]
	v_mfma_f32_16x16x32_bf16 v[26:29], v[134:137], v[200:203], v[26:29]
	v_mfma_f32_16x16x32_bf16 v[14:17], v[118:121], v[230:233], v[14:17]
	v_mfma_f32_16x16x32_bf16 v[10:13], v[134:137], v[230:233], v[10:13]
	s_setprio 0
	s_setprio 1
	s_setprio 0
	s_barrier
; #define PG8_STAGE(bufoff, gbase, voff) do { _Pragma("unroll") for (int _i = 0; _i < 2; ++_i) \
;         __builtin_amdgcn_global_load_lds((const unsigned*)((const char*)(gbase) + (voff)[_i]), (PG8_LAS unsigned*)(lds + (bufoff) + ldsw + _i * 8192), 16, 0, 0); } while (0)
; #define PG8_LDA(dst, b, h) do { _Pragma("unroll") for (int m = 0; m < 4; ++m) _Pragma("unroll") for (int k = 0; k < 2; ++k) dst[m][k] = *(const PG8_LAS bf16x8*)(lds + PG8_SA(b, h) + aoff + m * 2048 + k * 1024); } while (0)
; #define PG8_LDB(dst, b, h) do { _Pragma("unroll") for (int n = 0; n < 2; ++n) _Pragma("unroll") for (int k = 0; k < 2; ++k) dst[n][k] = *(const PG8_LAS bf16x8*)(lds + PG8_SB(b, h) + boff + n * 2048 + k * 1024); } while (0)
; #define PG8_MMA(ai, bj, At, Bt) do { __builtin_amdgcn_s_setprio(1); _Pragma("unroll") for (int m = 0; m < 4; ++m) _Pragma("unroll") for (int n = 0; n < 2; ++n) _Pragma("unroll") for (int k = 0; k < 2; ++k) \
;         acc[ai][bj][m][n] = __builtin_amdgcn_mfma_f32_16x16x32_bf16(Bt[n][k], At[m][k], acc[ai][bj][m][n], 0, 0, 0); __builtin_amdgcn_s_setprio(0); } while (0)
; #define PG8_WAIT_V(n) asm volatile("s_waitcnt vmcnt(" #n ")" ::: "memory")
; #define PG8_WAIT_L(n) asm volatile("s_waitcnt lgkmcnt(" #n ")" ::: "memory")
; #define PG8_BAR __builtin_amdgcn_s_barrier()
; #define PG8_SCHED __builtin_amdgcn_sched_barrier(0)
; template <class Epi, class Sched, bool ALIGN_EPI = false, bool SP2 = false>
; __device__ __forceinline__ void gemm_phase(PG8_LAS unsigned char* lds, const Gemm g, const Sched& S, const Epi& E) {
;     ...
;             PG8_LDB(B0, 1, 0); PG8_LDB(B1, 1, 1); PG8_SCHED; PG8_LDA(At, 1, 0); PG8_STAGE(PG8_SA(0, 1), a2 + hstep, voffA);
;             PG8_WAIT_V(8); PG8_WAIT_L(0); PG8_BAR; PG8_MMA(0, 0, At, B0); PG8_MMA(0, 1, At, B1); PG8_BAR; PG8_SCHED;
;             PG8_LDA(At, 1, 1); PG8_STAGE(PG8_SB(1, 0), b3, voffB); PG8_STAGE(PG8_SB(1, 1), b3 + hstep, voffB); PG8_STAGE(PG8_SA(1, 0), a3, voffA);
;             PG8_WAIT_V(8); PG8_WAIT_L(0); PG8_BAR; PG8_MMA(1, 0, At, B0); PG8_MMA(1, 1, At, B1); PG8_BAR; PG8_SCHED;
	s_add_i32 s47, 0, 0x1c000
	v_add_u32_e32 v134, s90, v177
	ds_read_b128 v[114:117], v134
	ds_read_b128 v[118:121], v134 offset:1024
	ds_read_b128 v[130:133], v134 offset:2048
	ds_read_b128 v[134:137], v134 offset:3072
	s_add_u32 s42, s42, 0x80000
	s_addc_u32 s43, s43, 0
	s_mov_b32 m0, s10
	v_lshl_add_u64 v[238:239], s[42:43], 0, v[158:159]
	ds_read_b128 v[180:183], v178 offset:32768
	ds_read_b128 v[184:187], v178 offset:33792
	ds_read_b128 v[188:191], v178 offset:34816
	ds_read_b128 v[192:195], v178 offset:35840
	ds_read_b128 v[196:199], v178 offset:36864
	ds_read_b128 v[200:203], v178 offset:37888
	ds_read_b128 v[208:211], v178 offset:38912
	ds_read_b128 v[230:233], v178 offset:39936
	global_load_lds_dwordx4 v[238:239], off
	v_lshl_add_u64 v[238:239], s[42:43], 0, v[156:157]
	s_mov_b32 m0, s11
	s_nop 0
	global_load_lds_dwordx4 v[238:239], off
	s_waitcnt vmcnt(6)
	s_waitcnt lgkmcnt(0)
	s_barrier
	s_setprio 1
	s_waitcnt lgkmcnt(0)
	v_mfma_f32_16x16x32_bf16 v[142:145], v[114:117], v[180:183], v[142:145]
	v_mfma_f32_16x16x32_bf16 v[138:141], v[130:133], v[180:183], v[138:141]
	v_mfma_f32_16x16x32_bf16 v[110:113], v[114:117], v[188:191], v[110:113]
	v_mfma_f32_16x16x32_bf16 v[106:109], v[130:133], v[188:191], v[106:109]
	v_mfma_f32_16x16x32_bf16 v[94:97], v[114:117], v[196:199], v[94:97]
	v_mfma_f32_16x16x32_bf16 v[90:93], v[130:133], v[196:199], v[90:93]
	v_mfma_f32_16x16x32_bf16 v[78:81], v[114:117], v[208:211], v[78:81]
	v_mfma_f32_16x16x32_bf16 v[74:77], v[130:133], v[208:211], v[74:77]
	v_mfma_f32_16x16x32_bf16 v[142:145], v[118:121], v[184:187], v[142:145]
	v_mfma_f32_16x16x32_bf16 v[138:141], v[134:137], v[184:187], v[138:141]
	v_mfma_f32_16x16x32_bf16 v[110:113], v[118:121], v[192:195], v[110:113]
	v_mfma_f32_16x16x32_bf16 v[106:109], v[134:137], v[192:195], v[106:109]
	v_mfma_f32_16x16x32_bf16 v[94:97], v[118:121], v[200:203], v[94:97]
	v_mfma_f32_16x16x32_bf16 v[90:93], v[134:137], v[200:203], v[90:93]
	v_mfma_f32_16x16x32_bf16 v[78:81], v[118:121], v[230:233], v[78:81]
	v_mfma_f32_16x16x32_bf16 v[74:77], v[134:137], v[230:233], v[74:77]
	s_setprio 0
	s_setprio 1
	s_setprio 0
	s_barrier
	s_add_i32 s42, s90, s6
	v_lshl_add_u64 v[204:205], v[204:205], 0, s[70:71]
	s_mov_b32 m0, s42
	ds_read_b128 v[180:183], v178 offset:49152
	ds_read_b128 v[184:187], v178 offset:50176
	ds_read_b128 v[188:191], v178 offset:51200
	ds_read_b128 v[192:195], v178 offset:52224
	ds_read_b128 v[196:199], v178 offset:53248
	ds_read_b128 v[200:203], v178 offset:54272
	ds_read_b128 v[208:211], v178 offset:55296
	ds_read_b128 v[230:233], v178 offset:56320
	global_load_lds_dwordx4 v[204:205], off
	s_add_i32 m0, s42, 0x2000
	s_add_u32 s40, s40, 0x80080
	v_lshl_add_u64 v[204:205], v[212:213], 0, s[70:71]
	s_addc_u32 s41, s41, 0
	s_add_i32 s42, s47, s6
	global_load_lds_dwordx4 v[204:205], off
	v_lshl_add_u64 v[204:205], s[40:41], 0, v[0:1]
	s_mov_b32 m0, s42
	s_nop 0
	v_lshl_add_u64 v[204:205], s[40:41], 0, v[154:155]
	s_add_i32 m0, s42, 0x2000
	s_nop 0
	v_lshl_add_u64 v[204:205], v[234:235], 0, s[70:71]
	s_mov_b32 m0, s13
	s_nop 0
	global_load_lds_dwordx4 v[204:205], off
	v_lshl_add_u64 v[204:205], v[236:237], 0, s[70:71]
	s_mov_b32 m0, s25
	s_nop 0
	global_load_lds_dwordx4 v[204:205], off
	s_waitcnt vmcnt(6)
	s_waitcnt lgkmcnt(0)
	s_barrier
	s_setprio 1
	s_waitcnt lgkmcnt(0)
	v_mfma_f32_16x16x32_bf16 v[62:65], v[114:117], v[180:183], v[62:65]
	v_mfma_f32_16x16x32_bf16 v[58:61], v[130:133], v[180:183], v[58:61]
	v_mfma_f32_16x16x32_bf16 v[46:49], v[114:117], v[188:191], v[46:49]
	v_mfma_f32_16x16x32_bf16 v[42:45], v[130:133], v[188:191], v[42:45]
	v_mfma_f32_16x16x32_bf16 v[30:33], v[114:117], v[196:199], v[30:33]
	v_mfma_f32_16x16x32_bf16 v[26:29], v[130:133], v[196:199], v[26:29]
	v_mfma_f32_16x16x32_bf16 v[14:17], v[114:117], v[208:211], v[14:17]
	v_mfma_f32_16x16x32_bf16 v[10:13], v[130:133], v[208:211], v[10:13]
	v_mfma_f32_16x16x32_bf16 v[62:65], v[118:121], v[184:187], v[62:65]
	v_mfma_f32_16x16x32_bf16 v[58:61], v[134:137], v[184:187], v[58:61]
	v_mfma_f32_16x16x32_bf16 v[46:49], v[118:121], v[192:195], v[46:49]
	v_mfma_f32_16x16x32_bf16 v[42:45], v[134:137], v[192:195], v[42:45]
	v_mfma_f32_16x16x32_bf16 v[30:33], v[118:121], v[200:203], v[30:33]
	v_mfma_f32_16x16x32_bf16 v[26:29], v[134:137], v[200:203], v[26:29]
	v_mfma_f32_16x16x32_bf16 v[14:17], v[118:121], v[230:233], v[14:17]
	v_mfma_f32_16x16x32_bf16 v[10:13], v[134:137], v[230:233], v[10:13]
	s_setprio 0
	s_setprio 1
	s_setprio 0
	s_barrier
	s_add_i32 s46, s46, 2
	s_add_u32 s34, s34, 0x100
	s_addc_u32 s35, s35, 0
	s_add_u32 s44, s44, 0x100
	s_addc_u32 s45, s45, 0
	s_cmp_gt_u32 s46, 29
	s_cbranch_scc0 .Ltail_loop
	s_branch .Ltail_join
